# top-k bisection: removed the now-dead per-block scalar zero/add pairs (32 SALU per full pass), on top of v021
# speedup vs baseline: 1.0047x; 1.0047x over previous
; DEVI void topk_select2(const unsigned (&kA)[64], const unsigned (&kB)[64], const bool two, const int ng, const int lim, bf16_t* mrowA, bf16_t* mrowB, const int lane) {
;     ...
;         int cA = 0, cB = 0;
;         if (!dA) {
;             cA = count_ge8(&kA[0], midA);
;             if (ng > 1) cA += count_ge8(&kA[8], midA);
;             if (ng > 2) cA += count_ge8(&kA[16], midA);
;             if (ng > 3) cA += count_ge8(&kA[24], midA);
;             if (ng > 4) cA += count_ge8(&kA[32], midA);
;             if (ng > 5) cA += count_ge8(&kA[40], midA);
;             if (ng > 6) cA += count_ge8(&kA[48], midA);
;             if (ng > 7) cA += count_ge8(&kA[56], midA);
;         }
.LBB0_492:
	v_mov_b32_e32 v235, 0
	v_mov_b32_e32 v236, 0
	v_mov_b32_e32 v237, 0
	v_mov_b32_e32 v238, 0
	s_waitcnt vmcnt(1)
	v_cndmask_b32_e64 v0, 0, 1, s[6:7]
	v_cmp_ne_u32_e64 s[0:1], 1, v0
	v_cndmask_b32_e64 v0, 0, 1, s[8:9]
	s_mov_b32 s39, 0
	s_andn2_b64 vcc, exec, s[6:7]
	v_cmp_ne_u32_e64 s[4:5], 1, v0
	s_cbranch_vccnz .LBB0_501
	s_and_b64 vcc, exec, s[4:5]
	v_cmp_ge_u32_e64 s[6:7], v90, s38
	v_cmp_ge_u32_e64 s[40:41], v91, s38
	v_cmp_ge_u32_e64 s[42:43], v86, s38
	v_cmp_ge_u32_e64 s[44:45], v87, s38
	v_addc_co_u32_e64 v235, s[6:7], 0, v235, s[6:7]
	v_cmp_ge_u32_e64 s[46:47], v88, s38
	v_addc_co_u32_e64 v236, s[40:41], 0, v236, s[40:41]
	v_cmp_ge_u32_e64 s[48:49], v89, s38
	v_addc_co_u32_e64 v235, s[42:43], 0, v235, s[42:43]
	v_cmp_ge_u32_e64 s[50:51], v84, s38
	v_addc_co_u32_e64 v236, s[44:45], 0, v236, s[44:45]
	v_cmp_ge_u32_e64 s[54:55], v85, s38
	v_addc_co_u32_e64 v235, s[46:47], 0, v235, s[46:47]
	v_addc_co_u32_e64 v236, s[48:49], 0, v236, s[48:49]
	v_addc_co_u32_e64 v235, s[50:51], 0, v235, s[50:51]
	v_addc_co_u32_e64 v236, s[54:55], 0, v236, s[54:55]
	s_cbranch_vccnz .LBB0_514
	v_cmp_ge_u32_e64 s[6:7], v94, s38
	v_cmp_ge_u32_e64 s[40:41], v95, s38
	v_cmp_ge_u32_e64 s[42:43], v82, s38
	v_cmp_ge_u32_e64 s[44:45], v83, s38
	v_addc_co_u32_e64 v235, s[6:7], 0, v235, s[6:7]
	v_cmp_ge_u32_e64 s[46:47], v98, s38
	v_addc_co_u32_e64 v236, s[40:41], 0, v236, s[40:41]
	v_cmp_ge_u32_e64 s[48:49], v99, s38
	v_addc_co_u32_e64 v235, s[42:43], 0, v235, s[42:43]
	v_cmp_ge_u32_e64 s[50:51], v96, s38
	v_addc_co_u32_e64 v236, s[44:45], 0, v236, s[44:45]
	v_cmp_ge_u32_e64 s[54:55], v97, s38
	v_addc_co_u32_e64 v235, s[46:47], 0, v235, s[46:47]
	v_addc_co_u32_e64 v236, s[48:49], 0, v236, s[48:49]
	v_addc_co_u32_e64 v235, s[50:51], 0, v235, s[50:51]
	v_addc_co_u32_e64 v236, s[54:55], 0, v236, s[54:55]
	s_andn2_b64 vcc, exec, s[10:11]
	s_cbranch_vccz .LBB0_515

; DEVI void topk_select2(const unsigned (&kA)[64], const unsigned (&kB)[64], const bool two, const int ng, const int lim, bf16_t* mrowA, bf16_t* mrowB, const int lane) {
;     ...
;             cA = count_ge8(&kA[0], midA);
;             if (ng > 1) cA += count_ge8(&kA[8], midA);
;             if (ng > 2) cA += count_ge8(&kA[16], midA);
;             if (ng > 3) cA += count_ge8(&kA[24], midA);
;             if (ng > 4) cA += count_ge8(&kA[32], midA);
;             if (ng > 5) cA += count_ge8(&kA[40], midA);
;             if (ng > 6) cA += count_ge8(&kA[48], midA);
;             if (ng > 7) cA += count_ge8(&kA[56], midA);
.LBB0_496:
	v_cmp_ge_u32_e64 s[6:7], v108, s38
	v_cmp_ge_u32_e64 s[40:41], v109, s38
	v_cmp_ge_u32_e64 s[42:43], v100, s38
	v_cmp_ge_u32_e64 s[44:45], v101, s38
	v_addc_co_u32_e64 v235, s[6:7], 0, v235, s[6:7]
	v_cmp_ge_u32_e64 s[46:47], v112, s38
	v_addc_co_u32_e64 v236, s[40:41], 0, v236, s[40:41]
	v_cmp_ge_u32_e64 s[48:49], v113, s38
	v_addc_co_u32_e64 v235, s[42:43], 0, v235, s[42:43]
	v_cmp_ge_u32_e64 s[50:51], v110, s38
	v_addc_co_u32_e64 v236, s[44:45], 0, v236, s[44:45]
	v_cmp_ge_u32_e64 s[54:55], v111, s38
	v_addc_co_u32_e64 v235, s[46:47], 0, v235, s[46:47]
	v_addc_co_u32_e64 v236, s[48:49], 0, v236, s[48:49]
	v_addc_co_u32_e64 v235, s[50:51], 0, v235, s[50:51]
	v_addc_co_u32_e64 v236, s[54:55], 0, v236, s[54:55]
	s_andn2_b64 vcc, exec, s[14:15]
	s_cbranch_vccz .LBB0_517

; DEVI void topk_select2(const unsigned (&kA)[64], const unsigned (&kB)[64], const bool two, const int ng, const int lim, bf16_t* mrowA, bf16_t* mrowB, const int lane) {
;     ...
;             cA = count_ge8(&kA[0], midA);
;             if (ng > 1) cA += count_ge8(&kA[8], midA);
;             if (ng > 2) cA += count_ge8(&kA[16], midA);
;             if (ng > 3) cA += count_ge8(&kA[24], midA);
;             if (ng > 4) cA += count_ge8(&kA[32], midA);
;             if (ng > 5) cA += count_ge8(&kA[40], midA);
;             if (ng > 6) cA += count_ge8(&kA[48], midA);
;             if (ng > 7) cA += count_ge8(&kA[56], midA);
.LBB0_498:
	v_cmp_ge_u32_e64 s[6:7], v136, s38
	v_cmp_ge_u32_e64 s[40:41], v137, s38
	v_cmp_ge_u32_e64 s[42:43], v128, s38
	v_cmp_ge_u32_e64 s[44:45], v129, s38
	v_addc_co_u32_e64 v235, s[6:7], 0, v235, s[6:7]
	v_cmp_ge_u32_e64 s[46:47], v134, s38
	v_addc_co_u32_e64 v236, s[40:41], 0, v236, s[40:41]
	v_cmp_ge_u32_e64 s[48:49], v135, s38
	v_addc_co_u32_e64 v235, s[42:43], 0, v235, s[42:43]
	v_cmp_ge_u32_e64 s[50:51], v132, s38
	v_addc_co_u32_e64 v236, s[44:45], 0, v236, s[44:45]
	v_cmp_ge_u32_e64 s[54:55], v133, s38
	v_addc_co_u32_e64 v235, s[46:47], 0, v235, s[46:47]
	v_addc_co_u32_e64 v236, s[48:49], 0, v236, s[48:49]
	v_addc_co_u32_e64 v235, s[50:51], 0, v235, s[50:51]
	v_addc_co_u32_e64 v236, s[54:55], 0, v236, s[54:55]
	s_andn2_b64 vcc, exec, s[18:19]
	s_cbranch_vccz .LBB0_519

; DEVI void topk_select2(const unsigned (&kA)[64], const unsigned (&kB)[64], const bool two, const int ng, const int lim, bf16_t* mrowA, bf16_t* mrowB, const int lane) {
;     ...
;         if (!dB) {
;             cB = count_ge8(&kB[0], midB);
;             if (ng > 1) cB += count_ge8(&kB[8], midB);
;             if (ng > 2) cB += count_ge8(&kB[16], midB);
;             if (ng > 3) cB += count_ge8(&kB[24], midB);
;             if (ng > 4) cB += count_ge8(&kB[32], midB);
;             if (ng > 5) cB += count_ge8(&kB[40], midB);
;             if (ng > 6) cB += count_ge8(&kB[48], midB);
;             if (ng > 7) cB += count_ge8(&kB[56], midB);
;         }
.LBB0_501:
	v_cndmask_b32_e64 v0, 0, 1, s[22:23]
	v_cmp_ne_u32_e64 s[6:7], 1, v0
	s_andn2_b64 vcc, exec, s[22:23]
	s_mov_b32 s22, 0
	s_cbranch_vccnz .LBB0_510
	s_and_b64 vcc, exec, s[4:5]
	v_cmp_ge_u32_e64 s[4:5], v38, s37
	v_cmp_ge_u32_e64 s[40:41], v39, s37
	v_cmp_ge_u32_e64 s[42:43], v34, s37
	v_cmp_ge_u32_e64 s[44:45], v35, s37
	v_addc_co_u32_e64 v237, s[4:5], 0, v237, s[4:5]
	v_cmp_ge_u32_e64 s[46:47], v40, s37
	v_addc_co_u32_e64 v238, s[40:41], 0, v238, s[40:41]
	v_cmp_ge_u32_e64 s[48:49], v41, s37
	v_addc_co_u32_e64 v237, s[42:43], 0, v237, s[42:43]
	v_cmp_ge_u32_e64 s[50:51], v36, s37
	v_addc_co_u32_e64 v238, s[44:45], 0, v238, s[44:45]
	v_cmp_ge_u32_e64 s[54:55], v37, s37
	v_addc_co_u32_e64 v237, s[46:47], 0, v237, s[46:47]
	v_addc_co_u32_e64 v238, s[48:49], 0, v238, s[48:49]
	v_addc_co_u32_e64 v237, s[50:51], 0, v237, s[50:51]
	v_addc_co_u32_e64 v238, s[54:55], 0, v238, s[54:55]
	s_cbranch_vccnz .LBB0_520
	v_cmp_ge_u32_e64 s[4:5], v44, s37
	v_cmp_ge_u32_e64 s[40:41], v45, s37
	v_cmp_ge_u32_e64 s[42:43], v42, s37
	v_cmp_ge_u32_e64 s[44:45], v43, s37
	v_addc_co_u32_e64 v237, s[4:5], 0, v237, s[4:5]
	v_cmp_ge_u32_e64 s[46:47], v48, s37
	v_addc_co_u32_e64 v238, s[40:41], 0, v238, s[40:41]
	v_cmp_ge_u32_e64 s[48:49], v49, s37
	v_addc_co_u32_e64 v237, s[42:43], 0, v237, s[42:43]
	v_cmp_ge_u32_e64 s[50:51], v46, s37
	v_addc_co_u32_e64 v238, s[44:45], 0, v238, s[44:45]
	v_cmp_ge_u32_e64 s[54:55], v47, s37
	v_addc_co_u32_e64 v237, s[46:47], 0, v237, s[46:47]
	v_addc_co_u32_e64 v238, s[48:49], 0, v238, s[48:49]
	v_addc_co_u32_e64 v237, s[50:51], 0, v237, s[50:51]
	v_addc_co_u32_e64 v238, s[54:55], 0, v238, s[54:55]
	s_andn2_b64 vcc, exec, s[10:11]
	s_cbranch_vccz .LBB0_521

; DEVI void topk_select2(const unsigned (&kA)[64], const unsigned (&kB)[64], const bool two, const int ng, const int lim, bf16_t* mrowA, bf16_t* mrowB, const int lane) {
;     ...
;             if (ng > 1) cB += count_ge8(&kB[8], midB);
;             if (ng > 2) cB += count_ge8(&kB[16], midB);
;             if (ng > 3) cB += count_ge8(&kB[24], midB);
;             if (ng > 4) cB += count_ge8(&kB[32], midB);
;             if (ng > 5) cB += count_ge8(&kB[40], midB);
;             if (ng > 6) cB += count_ge8(&kB[48], midB);
;             if (ng > 7) cB += count_ge8(&kB[56], midB);
.LBB0_505:
	v_cmp_ge_u32_e64 s[4:5], v60, s37
	v_cmp_ge_u32_e64 s[40:41], v61, s37
	v_cmp_ge_u32_e64 s[42:43], v58, s37
	v_cmp_ge_u32_e64 s[44:45], v59, s37
	v_addc_co_u32_e64 v237, s[4:5], 0, v237, s[4:5]
	v_cmp_ge_u32_e64 s[46:47], v64, s37
	v_addc_co_u32_e64 v238, s[40:41], 0, v238, s[40:41]
	v_cmp_ge_u32_e64 s[48:49], v65, s37
	v_addc_co_u32_e64 v237, s[42:43], 0, v237, s[42:43]
	v_cmp_ge_u32_e64 s[50:51], v62, s37
	v_addc_co_u32_e64 v238, s[44:45], 0, v238, s[44:45]
	v_cmp_ge_u32_e64 s[54:55], v63, s37
	v_addc_co_u32_e64 v237, s[46:47], 0, v237, s[46:47]
	v_addc_co_u32_e64 v238, s[48:49], 0, v238, s[48:49]
	v_addc_co_u32_e64 v237, s[50:51], 0, v237, s[50:51]
	v_addc_co_u32_e64 v238, s[54:55], 0, v238, s[54:55]
	s_andn2_b64 vcc, exec, s[14:15]
	s_cbranch_vccz .LBB0_523

; DEVI void topk_select2(const unsigned (&kA)[64], const unsigned (&kB)[64], const bool two, const int ng, const int lim, bf16_t* mrowA, bf16_t* mrowB, const int lane) {
;     ...
;             if (ng > 1) cB += count_ge8(&kB[8], midB);
;             if (ng > 2) cB += count_ge8(&kB[16], midB);
;             if (ng > 3) cB += count_ge8(&kB[24], midB);
;             if (ng > 4) cB += count_ge8(&kB[32], midB);
;             if (ng > 5) cB += count_ge8(&kB[40], midB);
;             if (ng > 6) cB += count_ge8(&kB[48], midB);
;             if (ng > 7) cB += count_ge8(&kB[56], midB);
.LBB0_507:
	v_cmp_ge_u32_e64 s[4:5], v74, s37
	v_cmp_ge_u32_e64 s[40:41], v75, s37
	v_cmp_ge_u32_e64 s[42:43], v68, s37
	v_cmp_ge_u32_e64 s[44:45], v69, s37
	v_addc_co_u32_e64 v237, s[4:5], 0, v237, s[4:5]
	v_cmp_ge_u32_e64 s[46:47], v70, s37
	v_addc_co_u32_e64 v238, s[40:41], 0, v238, s[40:41]
	v_cmp_ge_u32_e64 s[48:49], v71, s37
	v_addc_co_u32_e64 v237, s[42:43], 0, v237, s[42:43]
	v_cmp_ge_u32_e64 s[50:51], v30, s37
	v_addc_co_u32_e64 v238, s[44:45], 0, v238, s[44:45]
	v_cmp_ge_u32_e64 s[54:55], v31, s37
	v_addc_co_u32_e64 v237, s[46:47], 0, v237, s[46:47]
	v_addc_co_u32_e64 v238, s[48:49], 0, v238, s[48:49]
	v_addc_co_u32_e64 v237, s[50:51], 0, v237, s[50:51]
	v_addc_co_u32_e64 v238, s[54:55], 0, v238, s[54:55]
	s_andn2_b64 vcc, exec, s[18:19]
	s_cbranch_vccz .LBB0_525

; DEVI void topk_select2(const unsigned (&kA)[64], const unsigned (&kB)[64], const bool two, const int ng, const int lim, bf16_t* mrowA, bf16_t* mrowB, const int lane) {
;     ...
;         if (!dB) {
;             cB = count_ge8(&kB[0], midB);
;             if (ng > 1) cB += count_ge8(&kB[8], midB);
;             if (ng > 2) cB += count_ge8(&kB[16], midB);
;             if (ng > 3) cB += count_ge8(&kB[24], midB);
;             if (ng > 4) cB += count_ge8(&kB[32], midB);
;             if (ng > 5) cB += count_ge8(&kB[40], midB);
;             if (ng > 6) cB += count_ge8(&kB[48], midB);
;             if (ng > 7) cB += count_ge8(&kB[56], midB);
;         }
;         if (!dA) {
;             if (cA >= 256) { loA = midA; clA = cA; } else { hiA = midA; chA = cA; }
;             if (cA == 256) { TA = midA; needA = 0; dA = true; }
;             else if (hiA - loA == 1u) { TA = loA; needA = (clA == 256) ? 0 : (256 - chA); dA = true; }
;         }
;         if (!dB) {
;             if (cB >= 256) { loB = midB; clB = cB; } else { hiB = midB; chB = cB; }
;             if (cB == 256) { TB = midB; needB = 0; dB = true; }
;             else if (hiB - loB == 1u) { TB = loB; needB = (clB == 256) ? 0 : (256 - chB); dB = true; }
;         }
.LBB0_509:
	v_cmp_ge_u32_e64 s[4:5], v24, s37
	v_cmp_ge_u32_e64 s[40:41], v25, s37
	v_cmp_ge_u32_e64 s[42:43], v18, s37
	v_cmp_ge_u32_e64 s[44:45], v19, s37
	v_addc_co_u32_e64 v237, s[4:5], 0, v237, s[4:5]
	v_cmp_ge_u32_e64 s[46:47], v20, s37
	v_addc_co_u32_e64 v238, s[40:41], 0, v238, s[40:41]
	v_cmp_ge_u32_e64 s[48:49], v21, s37
	v_addc_co_u32_e64 v237, s[42:43], 0, v237, s[42:43]
	v_cmp_ge_u32_e64 s[50:51], v16, s37
	v_addc_co_u32_e64 v238, s[44:45], 0, v238, s[44:45]
	v_cmp_ge_u32_e64 s[54:55], v17, s37
	v_addc_co_u32_e64 v237, s[46:47], 0, v237, s[46:47]
	v_addc_co_u32_e64 v238, s[48:49], 0, v238, s[48:49]
	v_addc_co_u32_e64 v237, s[50:51], 0, v237, s[50:51]
	v_addc_co_u32_e64 v238, s[54:55], 0, v238, s[54:55]
.LBB0_510:
	v_add_u32_e32 v235, v235, v236
	v_add_u32_e32 v237, v237, v238
	v_lshl_add_u32 v239, v237, 16, v235
	s_nop 1
	v_add_u32_dpp v239, v239, v239 quad_perm:[1,0,3,2] row_mask:0xf bank_mask:0xf bound_ctrl:1
	s_nop 1
	v_add_u32_dpp v239, v239, v239 quad_perm:[2,3,0,1] row_mask:0xf bank_mask:0xf bound_ctrl:1
	s_nop 1
	v_add_u32_dpp v239, v239, v239 row_half_mirror row_mask:0xf bank_mask:0xf bound_ctrl:1
	s_nop 1
	v_add_u32_dpp v239, v239, v239 row_mirror row_mask:0xf bank_mask:0xf bound_ctrl:1
	s_nop 1
	v_readlane_b32 s2, v239, 0
	v_readlane_b32 s3, v239, 16
	v_readlane_b32 s23, v239, 32
	v_readlane_b32 s56, v239, 48
	s_add_i32 s2, s2, s3
	s_add_i32 s23, s23, s56
	s_add_i32 s2, s2, s23
	s_and_b32 s39, s2, 0xffff
	s_lshr_b32 s22, s2, 16
	s_and_b64 vcc, exec, s[0:1]
	s_mov_b64 s[4:5], -1
	s_cbranch_vccnz .LBB0_526
	s_cmpk_gt_i32 s39, 0xff
	s_cselect_b32 s31, s31, s39
	s_cselect_b32 s24, s39, s24
	s_cselect_b32 s26, s26, s38
	s_cselect_b32 s29, s38, s29
	s_cmpk_eq_i32 s39, 0x100
	s_cbranch_scc1 .LBB0_531
	s_sub_i32 s0, s26, s29
	s_cmp_lg_u32 s0, 1
	s_mov_b64 s[0:1], 0
	s_cbranch_scc1 .LBB0_527
	s_sub_i32 s0, 0x100, s31
	s_cmpk_lg_i32 s24, 0x100
	s_cselect_b32 s72, s0, 0
	s_mov_b64 s[0:1], -1
	s_mov_b32 s73, s29
	s_and_b64 vcc, exec, s[6:7]
	s_cbranch_vccnz .LBB0_485
	s_branch .LBB0_528

; DEVI void topk_select2(const unsigned (&kA)[64], const unsigned (&kB)[64], const bool two, const int ng, const int lim, bf16_t* mrowA, bf16_t* mrowB, const int lane) {
;     ...
;             cA = count_ge8(&kA[0], midA);
;             if (ng > 1) cA += count_ge8(&kA[8], midA);
;             if (ng > 2) cA += count_ge8(&kA[16], midA);
;             if (ng > 3) cA += count_ge8(&kA[24], midA);
;             if (ng > 4) cA += count_ge8(&kA[32], midA);
;             if (ng > 5) cA += count_ge8(&kA[40], midA);
;             if (ng > 6) cA += count_ge8(&kA[48], midA);
;             if (ng > 7) cA += count_ge8(&kA[56], midA);
.LBB0_515:
	v_cmp_ge_u32_e64 s[6:7], v102, s38
	v_cmp_ge_u32_e64 s[40:41], v103, s38
	v_cmp_ge_u32_e64 s[42:43], v92, s38
	v_cmp_ge_u32_e64 s[44:45], v93, s38
	v_addc_co_u32_e64 v235, s[6:7], 0, v235, s[6:7]
	v_cmp_ge_u32_e64 s[46:47], v106, s38
	v_addc_co_u32_e64 v236, s[40:41], 0, v236, s[40:41]
	v_cmp_ge_u32_e64 s[48:49], v107, s38
	v_addc_co_u32_e64 v235, s[42:43], 0, v235, s[42:43]
	v_cmp_ge_u32_e64 s[50:51], v104, s38
	v_addc_co_u32_e64 v236, s[44:45], 0, v236, s[44:45]
	v_cmp_ge_u32_e64 s[54:55], v105, s38
	v_addc_co_u32_e64 v235, s[46:47], 0, v235, s[46:47]
	v_addc_co_u32_e64 v236, s[48:49], 0, v236, s[48:49]
	v_addc_co_u32_e64 v235, s[50:51], 0, v235, s[50:51]
	v_addc_co_u32_e64 v236, s[54:55], 0, v236, s[54:55]
	s_andn2_b64 vcc, exec, s[12:13]
	s_cbranch_vccz .LBB0_496

; DEVI void topk_select2(const unsigned (&kA)[64], const unsigned (&kB)[64], const bool two, const int ng, const int lim, bf16_t* mrowA, bf16_t* mrowB, const int lane) {
;     ...
;             cA = count_ge8(&kA[0], midA);
;             if (ng > 1) cA += count_ge8(&kA[8], midA);
;             if (ng > 2) cA += count_ge8(&kA[16], midA);
;             if (ng > 3) cA += count_ge8(&kA[24], midA);
;             if (ng > 4) cA += count_ge8(&kA[32], midA);
;             if (ng > 5) cA += count_ge8(&kA[40], midA);
;             if (ng > 6) cA += count_ge8(&kA[48], midA);
;             if (ng > 7) cA += count_ge8(&kA[56], midA);
.LBB0_517:
	v_cmp_ge_u32_e64 s[6:7], v144, s38
	v_cmp_ge_u32_e64 s[40:41], v145, s38
	v_cmp_ge_u32_e64 s[42:43], v142, s38
	v_cmp_ge_u32_e64 s[44:45], v143, s38
	v_addc_co_u32_e64 v235, s[6:7], 0, v235, s[6:7]
	v_cmp_ge_u32_e64 s[46:47], v140, s38
	v_addc_co_u32_e64 v236, s[40:41], 0, v236, s[40:41]
	v_cmp_ge_u32_e64 s[48:49], v141, s38
	v_addc_co_u32_e64 v235, s[42:43], 0, v235, s[42:43]
	v_cmp_ge_u32_e64 s[50:51], v138, s38
	v_addc_co_u32_e64 v236, s[44:45], 0, v236, s[44:45]
	v_cmp_ge_u32_e64 s[54:55], v139, s38
	v_addc_co_u32_e64 v235, s[46:47], 0, v235, s[46:47]
	v_addc_co_u32_e64 v236, s[48:49], 0, v236, s[48:49]
	v_addc_co_u32_e64 v235, s[50:51], 0, v235, s[50:51]
	v_addc_co_u32_e64 v236, s[54:55], 0, v236, s[54:55]
	s_andn2_b64 vcc, exec, s[16:17]
	s_cbranch_vccz .LBB0_498

; DEVI void topk_select2(const unsigned (&kA)[64], const unsigned (&kB)[64], const bool two, const int ng, const int lim, bf16_t* mrowA, bf16_t* mrowB, const int lane) {
;     ...
;             cA = count_ge8(&kA[0], midA);
;             if (ng > 1) cA += count_ge8(&kA[8], midA);
;             if (ng > 2) cA += count_ge8(&kA[16], midA);
;             if (ng > 3) cA += count_ge8(&kA[24], midA);
;             if (ng > 4) cA += count_ge8(&kA[32], midA);
;             if (ng > 5) cA += count_ge8(&kA[40], midA);
;             if (ng > 6) cA += count_ge8(&kA[48], midA);
;             if (ng > 7) cA += count_ge8(&kA[56], midA);
.LBB0_519:
	v_cmp_ge_u32_e64 s[6:7], v130, s38
	v_cmp_ge_u32_e64 s[40:41], v131, s38
	v_cmp_ge_u32_e64 s[42:43], v120, s38
	v_cmp_ge_u32_e64 s[44:45], v121, s38
	v_addc_co_u32_e64 v235, s[6:7], 0, v235, s[6:7]
	v_cmp_ge_u32_e64 s[46:47], v126, s38
	v_addc_co_u32_e64 v236, s[40:41], 0, v236, s[40:41]
	v_cmp_ge_u32_e64 s[48:49], v127, s38
	v_addc_co_u32_e64 v235, s[42:43], 0, v235, s[42:43]
	v_cmp_ge_u32_e64 s[50:51], v124, s38
	v_addc_co_u32_e64 v236, s[44:45], 0, v236, s[44:45]
	v_cmp_ge_u32_e64 s[54:55], v125, s38
	v_addc_co_u32_e64 v235, s[46:47], 0, v235, s[46:47]
	v_addc_co_u32_e64 v236, s[48:49], 0, v236, s[48:49]
	v_addc_co_u32_e64 v235, s[50:51], 0, v235, s[50:51]
	v_addc_co_u32_e64 v236, s[54:55], 0, v236, s[54:55]
	s_andn2_b64 vcc, exec, s[20:21]
	s_cbranch_vccz .LBB0_500
	s_branch .LBB0_501

; DEVI void topk_select2(const unsigned (&kA)[64], const unsigned (&kB)[64], const bool two, const int ng, const int lim, bf16_t* mrowA, bf16_t* mrowB, const int lane) {
;     ...
;             if (ng > 1) cB += count_ge8(&kB[8], midB);
;             if (ng > 2) cB += count_ge8(&kB[16], midB);
;             if (ng > 3) cB += count_ge8(&kB[24], midB);
;             if (ng > 4) cB += count_ge8(&kB[32], midB);
;             if (ng > 5) cB += count_ge8(&kB[40], midB);
;             if (ng > 6) cB += count_ge8(&kB[48], midB);
;             if (ng > 7) cB += count_ge8(&kB[56], midB);
.LBB0_521:
	v_cmp_ge_u32_e64 s[4:5], v52, s37
	v_cmp_ge_u32_e64 s[40:41], v53, s37
	v_cmp_ge_u32_e64 s[42:43], v50, s37
	v_cmp_ge_u32_e64 s[44:45], v51, s37
	v_addc_co_u32_e64 v237, s[4:5], 0, v237, s[4:5]
	v_cmp_ge_u32_e64 s[46:47], v56, s37
	v_addc_co_u32_e64 v238, s[40:41], 0, v238, s[40:41]
	v_cmp_ge_u32_e64 s[48:49], v57, s37
	v_addc_co_u32_e64 v237, s[42:43], 0, v237, s[42:43]
	v_cmp_ge_u32_e64 s[50:51], v54, s37
	v_addc_co_u32_e64 v238, s[44:45], 0, v238, s[44:45]
	v_cmp_ge_u32_e64 s[54:55], v55, s37
	v_addc_co_u32_e64 v237, s[46:47], 0, v237, s[46:47]
	v_addc_co_u32_e64 v238, s[48:49], 0, v238, s[48:49]
	v_addc_co_u32_e64 v237, s[50:51], 0, v237, s[50:51]
	v_addc_co_u32_e64 v238, s[54:55], 0, v238, s[54:55]
	s_andn2_b64 vcc, exec, s[12:13]
	s_cbranch_vccz .LBB0_505

; DEVI void topk_select2(const unsigned (&kA)[64], const unsigned (&kB)[64], const bool two, const int ng, const int lim, bf16_t* mrowA, bf16_t* mrowB, const int lane) {
;     ...
;             if (ng > 1) cB += count_ge8(&kB[8], midB);
;             if (ng > 2) cB += count_ge8(&kB[16], midB);
;             if (ng > 3) cB += count_ge8(&kB[24], midB);
;             if (ng > 4) cB += count_ge8(&kB[32], midB);
;             if (ng > 5) cB += count_ge8(&kB[40], midB);
;             if (ng > 6) cB += count_ge8(&kB[48], midB);
;             if (ng > 7) cB += count_ge8(&kB[56], midB);
.LBB0_523:
	v_cmp_ge_u32_e64 s[4:5], v80, s37
	v_cmp_ge_u32_e64 s[40:41], v81, s37
	v_cmp_ge_u32_e64 s[42:43], v78, s37
	v_cmp_ge_u32_e64 s[44:45], v79, s37
	v_addc_co_u32_e64 v237, s[4:5], 0, v237, s[4:5]
	v_cmp_ge_u32_e64 s[46:47], v76, s37
	v_addc_co_u32_e64 v238, s[40:41], 0, v238, s[40:41]
	v_cmp_ge_u32_e64 s[48:49], v77, s37
	v_addc_co_u32_e64 v237, s[42:43], 0, v237, s[42:43]
	v_cmp_ge_u32_e64 s[50:51], v72, s37
	v_addc_co_u32_e64 v238, s[44:45], 0, v238, s[44:45]
	v_cmp_ge_u32_e64 s[54:55], v73, s37
	v_addc_co_u32_e64 v237, s[46:47], 0, v237, s[46:47]
	v_addc_co_u32_e64 v238, s[48:49], 0, v238, s[48:49]
	v_addc_co_u32_e64 v237, s[50:51], 0, v237, s[50:51]
	v_addc_co_u32_e64 v238, s[54:55], 0, v238, s[54:55]
	s_andn2_b64 vcc, exec, s[16:17]
	s_cbranch_vccz .LBB0_507

; DEVI void topk_select2(const unsigned (&kA)[64], const unsigned (&kB)[64], const bool two, const int ng, const int lim, bf16_t* mrowA, bf16_t* mrowB, const int lane) {
;     ...
;             if (ng > 1) cB += count_ge8(&kB[8], midB);
;             if (ng > 2) cB += count_ge8(&kB[16], midB);
;             if (ng > 3) cB += count_ge8(&kB[24], midB);
;             if (ng > 4) cB += count_ge8(&kB[32], midB);
;             if (ng > 5) cB += count_ge8(&kB[40], midB);
;             if (ng > 6) cB += count_ge8(&kB[48], midB);
;             if (ng > 7) cB += count_ge8(&kB[56], midB);
.LBB0_525:
	v_cmp_ge_u32_e64 s[4:5], v66, s37
	v_cmp_ge_u32_e64 s[40:41], v67, s37
	v_cmp_ge_u32_e64 s[42:43], v26, s37
	v_cmp_ge_u32_e64 s[44:45], v27, s37
	v_addc_co_u32_e64 v237, s[4:5], 0, v237, s[4:5]
	v_cmp_ge_u32_e64 s[46:47], v28, s37
	v_addc_co_u32_e64 v238, s[40:41], 0, v238, s[40:41]
	v_cmp_ge_u32_e64 s[48:49], v29, s37
	v_addc_co_u32_e64 v237, s[42:43], 0, v237, s[42:43]
	v_cmp_ge_u32_e64 s[50:51], v22, s37
	v_addc_co_u32_e64 v238, s[44:45], 0, v238, s[44:45]
	v_cmp_ge_u32_e64 s[54:55], v23, s37
	v_addc_co_u32_e64 v237, s[46:47], 0, v237, s[46:47]
	v_addc_co_u32_e64 v238, s[48:49], 0, v238, s[48:49]
	v_addc_co_u32_e64 v237, s[50:51], 0, v237, s[50:51]
	v_addc_co_u32_e64 v238, s[54:55], 0, v238, s[54:55]
	s_andn2_b64 vcc, exec, s[20:21]
	s_cbranch_vccz .LBB0_509
	s_branch .LBB0_510
